# prologue de-serialisation: the silu(c)->LDS fill at kernel start (36-trip loop, one dependent global load + kernarg s_load per trip) now issues all 36 loads and waits once
# speedup vs baseline: 1.0069x; 1.0060x over previous
; __device__ __forceinline__ int otid() { int t = threadIdx.x; asm volatile("" : "+v"(t)); return t; }
; __device__ __forceinline__ float silu_f(float x) { return x * __builtin_amdgcn_rcpf(1.f + __expf(-x)); }
; __device__ __forceinline__ void phase_prologue(const KArgs& A, LAS unsigned char* lds, int wave, int lane) {
;     ...
;     for (int i = otid(); i < 9 * 2048; i += 512) { const int v = i >> 11, k = i & 2047; const float x = v < 8 ? A.in[1][v * 2048 + k] : A.in[3][k]; sl[i] = silu_f(x); }
.LBB0_387:
	s_load_dwordx2 s[6:7], s[56:57], 0x8
	s_load_dwordx2 s[8:9], s[56:57], 0x18
	v_lshlrev_b32_e32 v2, 2, v184
	v_add_u32_e32 v3, 0x10000, v2
	s_waitcnt lgkmcnt(0)
	global_load_dword v10, v2, s[6:7]
	global_load_dword v11, v2, s[6:7] offset:2048
	s_add_u32 s6, s6, 0x1000
	s_addc_u32 s7, s7, 0
	global_load_dword v12, v2, s[6:7]
	global_load_dword v13, v2, s[6:7] offset:2048
	s_add_u32 s6, s6, 0x1000
	s_addc_u32 s7, s7, 0
	global_load_dword v14, v2, s[6:7]
	global_load_dword v15, v2, s[6:7] offset:2048
	s_add_u32 s6, s6, 0x1000
	s_addc_u32 s7, s7, 0
	global_load_dword v16, v2, s[6:7]
	global_load_dword v17, v2, s[6:7] offset:2048
	s_add_u32 s6, s6, 0x1000
	s_addc_u32 s7, s7, 0
	global_load_dword v18, v2, s[6:7]
	global_load_dword v19, v2, s[6:7] offset:2048
	s_add_u32 s6, s6, 0x1000
	s_addc_u32 s7, s7, 0
	global_load_dword v20, v2, s[6:7]
	global_load_dword v21, v2, s[6:7] offset:2048
	s_add_u32 s6, s6, 0x1000
	s_addc_u32 s7, s7, 0
	global_load_dword v22, v2, s[6:7]
	global_load_dword v23, v2, s[6:7] offset:2048
	s_add_u32 s6, s6, 0x1000
	s_addc_u32 s7, s7, 0
	global_load_dword v24, v2, s[6:7]
	global_load_dword v25, v2, s[6:7] offset:2048
	s_add_u32 s6, s6, 0x1000
	s_addc_u32 s7, s7, 0
	global_load_dword v26, v2, s[6:7]
	global_load_dword v27, v2, s[6:7] offset:2048
	s_add_u32 s6, s6, 0x1000
	s_addc_u32 s7, s7, 0
	global_load_dword v28, v2, s[6:7]
	global_load_dword v29, v2, s[6:7] offset:2048
	s_add_u32 s6, s6, 0x1000
	s_addc_u32 s7, s7, 0
	global_load_dword v30, v2, s[6:7]
	global_load_dword v31, v2, s[6:7] offset:2048
	s_add_u32 s6, s6, 0x1000
	s_addc_u32 s7, s7, 0
	global_load_dword v32, v2, s[6:7]
	global_load_dword v33, v2, s[6:7] offset:2048
	s_add_u32 s6, s6, 0x1000
	s_addc_u32 s7, s7, 0
	global_load_dword v34, v2, s[6:7]
	global_load_dword v35, v2, s[6:7] offset:2048
	s_add_u32 s6, s6, 0x1000
	s_addc_u32 s7, s7, 0
	global_load_dword v36, v2, s[6:7]
	global_load_dword v37, v2, s[6:7] offset:2048
	s_add_u32 s6, s6, 0x1000
	s_addc_u32 s7, s7, 0
	global_load_dword v38, v2, s[6:7]
	global_load_dword v39, v2, s[6:7] offset:2048
	s_add_u32 s6, s6, 0x1000
	s_addc_u32 s7, s7, 0
	global_load_dword v40, v2, s[6:7]
	global_load_dword v41, v2, s[6:7] offset:2048
	global_load_dword v42, v2, s[8:9]
	global_load_dword v43, v2, s[8:9] offset:2048
	s_add_u32 s8, s8, 0x1000
	s_addc_u32 s9, s9, 0
	global_load_dword v44, v2, s[8:9]
	global_load_dword v45, v2, s[8:9] offset:2048
	s_waitcnt vmcnt(0)
; __device__ __forceinline__ int otid() { int t = threadIdx.x; asm volatile("" : "+v"(t)); return t; }
; __device__ __forceinline__ float silu_f(float x) { return x * __builtin_amdgcn_rcpf(1.f + __expf(-x)); }
; __device__ __forceinline__ void phase_prologue(const KArgs& A, LAS unsigned char* lds, int wave, int lane) {
;     ...
;     for (int i = otid(); i < 9 * 2048; i += 512) { const int v = i >> 11, k = i & 2047; const float x = v < 8 ? A.in[1][v * 2048 + k] : A.in[3][k]; sl[i] = silu_f(x); }
	v_mul_f32_e32 v7, 0xbfb8aa3b, v10
	v_exp_f32_e32 v7, v7
	s_nop 0
	v_add_f32_e32 v8, 1.0, v7
	v_rcp_f32_e32 v7, v8
	s_nop 0
	v_mul_f32_e32 v10, v10, v7
	ds_write_b32 v2, v10
	v_mul_f32_e32 v7, 0xbfb8aa3b, v11
	v_exp_f32_e32 v7, v7
	s_nop 0
	v_add_f32_e32 v8, 1.0, v7
	v_rcp_f32_e32 v7, v8
	s_nop 0
	v_mul_f32_e32 v11, v11, v7
	ds_write_b32 v2, v11 offset:2048
	v_mul_f32_e32 v7, 0xbfb8aa3b, v12
	v_exp_f32_e32 v7, v7
	s_nop 0
	v_add_f32_e32 v8, 1.0, v7
	v_rcp_f32_e32 v7, v8
	s_nop 0
	v_mul_f32_e32 v12, v12, v7
	ds_write_b32 v2, v12 offset:4096
	v_mul_f32_e32 v7, 0xbfb8aa3b, v13
	v_exp_f32_e32 v7, v7
	s_nop 0
	v_add_f32_e32 v8, 1.0, v7
	v_rcp_f32_e32 v7, v8
	s_nop 0
	v_mul_f32_e32 v13, v13, v7
	ds_write_b32 v2, v13 offset:6144
	v_mul_f32_e32 v7, 0xbfb8aa3b, v14
	v_exp_f32_e32 v7, v7
	s_nop 0
	v_add_f32_e32 v8, 1.0, v7
	v_rcp_f32_e32 v7, v8
	s_nop 0
	v_mul_f32_e32 v14, v14, v7
	ds_write_b32 v2, v14 offset:8192
	v_mul_f32_e32 v7, 0xbfb8aa3b, v15
	v_exp_f32_e32 v7, v7
	s_nop 0
	v_add_f32_e32 v8, 1.0, v7
	v_rcp_f32_e32 v7, v8
	s_nop 0
	v_mul_f32_e32 v15, v15, v7
	ds_write_b32 v2, v15 offset:10240
	v_mul_f32_e32 v7, 0xbfb8aa3b, v16
	v_exp_f32_e32 v7, v7
	s_nop 0
	v_add_f32_e32 v8, 1.0, v7
	v_rcp_f32_e32 v7, v8
	s_nop 0
	v_mul_f32_e32 v16, v16, v7
	ds_write_b32 v2, v16 offset:12288
	v_mul_f32_e32 v7, 0xbfb8aa3b, v17
	v_exp_f32_e32 v7, v7
	s_nop 0
	v_add_f32_e32 v8, 1.0, v7
	v_rcp_f32_e32 v7, v8
	s_nop 0
	v_mul_f32_e32 v17, v17, v7
	ds_write_b32 v2, v17 offset:14336
	v_mul_f32_e32 v7, 0xbfb8aa3b, v18
	v_exp_f32_e32 v7, v7
	s_nop 0
	v_add_f32_e32 v8, 1.0, v7
	v_rcp_f32_e32 v7, v8
	s_nop 0
	v_mul_f32_e32 v18, v18, v7
	ds_write_b32 v2, v18 offset:16384
	v_mul_f32_e32 v7, 0xbfb8aa3b, v19
	v_exp_f32_e32 v7, v7
	s_nop 0
	v_add_f32_e32 v8, 1.0, v7
	v_rcp_f32_e32 v7, v8
	s_nop 0
	v_mul_f32_e32 v19, v19, v7
	ds_write_b32 v2, v19 offset:18432
	v_mul_f32_e32 v7, 0xbfb8aa3b, v20
	v_exp_f32_e32 v7, v7
	s_nop 0
	v_add_f32_e32 v8, 1.0, v7
	v_rcp_f32_e32 v7, v8
	s_nop 0
	v_mul_f32_e32 v20, v20, v7
	ds_write_b32 v2, v20 offset:20480
	v_mul_f32_e32 v7, 0xbfb8aa3b, v21
	v_exp_f32_e32 v7, v7
	s_nop 0
	v_add_f32_e32 v8, 1.0, v7
	v_rcp_f32_e32 v7, v8
	s_nop 0
	v_mul_f32_e32 v21, v21, v7
	ds_write_b32 v2, v21 offset:22528
	v_mul_f32_e32 v7, 0xbfb8aa3b, v22
	v_exp_f32_e32 v7, v7
	s_nop 0
	v_add_f32_e32 v8, 1.0, v7
	v_rcp_f32_e32 v7, v8
	s_nop 0
	v_mul_f32_e32 v22, v22, v7
	ds_write_b32 v2, v22 offset:24576
	v_mul_f32_e32 v7, 0xbfb8aa3b, v23
	v_exp_f32_e32 v7, v7
	s_nop 0
	v_add_f32_e32 v8, 1.0, v7
	v_rcp_f32_e32 v7, v8
	s_nop 0
	v_mul_f32_e32 v23, v23, v7
	ds_write_b32 v2, v23 offset:26624
	v_mul_f32_e32 v7, 0xbfb8aa3b, v24
	v_exp_f32_e32 v7, v7
	s_nop 0
	v_add_f32_e32 v8, 1.0, v7
	v_rcp_f32_e32 v7, v8
	s_nop 0
	v_mul_f32_e32 v24, v24, v7
	ds_write_b32 v2, v24 offset:28672
	v_mul_f32_e32 v7, 0xbfb8aa3b, v25
	v_exp_f32_e32 v7, v7
	s_nop 0
	v_add_f32_e32 v8, 1.0, v7
	v_rcp_f32_e32 v7, v8
	s_nop 0
	v_mul_f32_e32 v25, v25, v7
	ds_write_b32 v2, v25 offset:30720
	v_mul_f32_e32 v7, 0xbfb8aa3b, v26
	v_exp_f32_e32 v7, v7
	s_nop 0
	v_add_f32_e32 v8, 1.0, v7
	v_rcp_f32_e32 v7, v8
	s_nop 0
	v_mul_f32_e32 v26, v26, v7
	ds_write_b32 v2, v26 offset:32768
	v_mul_f32_e32 v7, 0xbfb8aa3b, v27
	v_exp_f32_e32 v7, v7
	s_nop 0
	v_add_f32_e32 v8, 1.0, v7
	v_rcp_f32_e32 v7, v8
	s_nop 0
	v_mul_f32_e32 v27, v27, v7
	ds_write_b32 v2, v27 offset:34816
	v_mul_f32_e32 v7, 0xbfb8aa3b, v28
	v_exp_f32_e32 v7, v7
	s_nop 0
	v_add_f32_e32 v8, 1.0, v7
	v_rcp_f32_e32 v7, v8
	s_nop 0
	v_mul_f32_e32 v28, v28, v7
	ds_write_b32 v2, v28 offset:36864
	v_mul_f32_e32 v7, 0xbfb8aa3b, v29
	v_exp_f32_e32 v7, v7
	s_nop 0
	v_add_f32_e32 v8, 1.0, v7
	v_rcp_f32_e32 v7, v8
	s_nop 0
	v_mul_f32_e32 v29, v29, v7
	ds_write_b32 v2, v29 offset:38912
	v_mul_f32_e32 v7, 0xbfb8aa3b, v30
	v_exp_f32_e32 v7, v7
	s_nop 0
	v_add_f32_e32 v8, 1.0, v7
	v_rcp_f32_e32 v7, v8
	s_nop 0
	v_mul_f32_e32 v30, v30, v7
	ds_write_b32 v2, v30 offset:40960
	v_mul_f32_e32 v7, 0xbfb8aa3b, v31
	v_exp_f32_e32 v7, v7
	s_nop 0
	v_add_f32_e32 v8, 1.0, v7
	v_rcp_f32_e32 v7, v8
	s_nop 0
	v_mul_f32_e32 v31, v31, v7
	ds_write_b32 v2, v31 offset:43008
	v_mul_f32_e32 v7, 0xbfb8aa3b, v32
	v_exp_f32_e32 v7, v7
	s_nop 0
	v_add_f32_e32 v8, 1.0, v7
	v_rcp_f32_e32 v7, v8
	s_nop 0
	v_mul_f32_e32 v32, v32, v7
	ds_write_b32 v2, v32 offset:45056
	v_mul_f32_e32 v7, 0xbfb8aa3b, v33
	v_exp_f32_e32 v7, v7
	s_nop 0
	v_add_f32_e32 v8, 1.0, v7
	v_rcp_f32_e32 v7, v8
	s_nop 0
	v_mul_f32_e32 v33, v33, v7
	ds_write_b32 v2, v33 offset:47104
	v_mul_f32_e32 v7, 0xbfb8aa3b, v34
	v_exp_f32_e32 v7, v7
	s_nop 0
	v_add_f32_e32 v8, 1.0, v7
	v_rcp_f32_e32 v7, v8
	s_nop 0
	v_mul_f32_e32 v34, v34, v7
	ds_write_b32 v2, v34 offset:49152
	v_mul_f32_e32 v7, 0xbfb8aa3b, v35
	v_exp_f32_e32 v7, v7
	s_nop 0
	v_add_f32_e32 v8, 1.0, v7
	v_rcp_f32_e32 v7, v8
	s_nop 0
	v_mul_f32_e32 v35, v35, v7
	ds_write_b32 v2, v35 offset:51200
	v_mul_f32_e32 v7, 0xbfb8aa3b, v36
	v_exp_f32_e32 v7, v7
	s_nop 0
	v_add_f32_e32 v8, 1.0, v7
	v_rcp_f32_e32 v7, v8
	s_nop 0
	v_mul_f32_e32 v36, v36, v7
	ds_write_b32 v2, v36 offset:53248
	v_mul_f32_e32 v7, 0xbfb8aa3b, v37
	v_exp_f32_e32 v7, v7
	s_nop 0
	v_add_f32_e32 v8, 1.0, v7
	v_rcp_f32_e32 v7, v8
	s_nop 0
	v_mul_f32_e32 v37, v37, v7
	ds_write_b32 v2, v37 offset:55296
	v_mul_f32_e32 v7, 0xbfb8aa3b, v38
	v_exp_f32_e32 v7, v7
	s_nop 0
	v_add_f32_e32 v8, 1.0, v7
	v_rcp_f32_e32 v7, v8
	s_nop 0
	v_mul_f32_e32 v38, v38, v7
	ds_write_b32 v2, v38 offset:57344
	v_mul_f32_e32 v7, 0xbfb8aa3b, v39
	v_exp_f32_e32 v7, v7
	s_nop 0
	v_add_f32_e32 v8, 1.0, v7
	v_rcp_f32_e32 v7, v8
	s_nop 0
	v_mul_f32_e32 v39, v39, v7
	ds_write_b32 v2, v39 offset:59392
	v_mul_f32_e32 v7, 0xbfb8aa3b, v40
	v_exp_f32_e32 v7, v7
	s_nop 0
	v_add_f32_e32 v8, 1.0, v7
	v_rcp_f32_e32 v7, v8
	s_nop 0
	v_mul_f32_e32 v40, v40, v7
	ds_write_b32 v2, v40 offset:61440
	v_mul_f32_e32 v7, 0xbfb8aa3b, v41
	v_exp_f32_e32 v7, v7
	s_nop 0
	v_add_f32_e32 v8, 1.0, v7
	v_rcp_f32_e32 v7, v8
	s_nop 0
	v_mul_f32_e32 v41, v41, v7
	ds_write_b32 v2, v41 offset:63488
	v_mul_f32_e32 v7, 0xbfb8aa3b, v42
	v_exp_f32_e32 v7, v7
	s_nop 0
	v_add_f32_e32 v8, 1.0, v7
	v_rcp_f32_e32 v7, v8
	s_nop 0
	v_mul_f32_e32 v42, v42, v7
	ds_write_b32 v3, v42
	v_mul_f32_e32 v7, 0xbfb8aa3b, v43
	v_exp_f32_e32 v7, v7
	s_nop 0
	v_add_f32_e32 v8, 1.0, v7
	v_rcp_f32_e32 v7, v8
	s_nop 0
	v_mul_f32_e32 v43, v43, v7
	ds_write_b32 v3, v43 offset:2048
	v_mul_f32_e32 v7, 0xbfb8aa3b, v44
	v_exp_f32_e32 v7, v7
	s_nop 0
	v_add_f32_e32 v8, 1.0, v7
	v_rcp_f32_e32 v7, v8
	s_nop 0
	v_mul_f32_e32 v44, v44, v7
	ds_write_b32 v3, v44 offset:4096
	v_mul_f32_e32 v7, 0xbfb8aa3b, v45
	v_exp_f32_e32 v7, v7
	s_nop 0
	v_add_f32_e32 v8, 1.0, v7
	v_rcp_f32_e32 v7, v8
	s_nop 0
	v_mul_f32_e32 v45, v45, v7
	ds_write_b32 v3, v45 offset:6144
